# streamer items: decay/k/q loads issued together and the v + state loads issued before waiting (2 fewer memory round trips per sample-state item), with 8192 weight items per recurrence phase moved to t
# baseline (speedup 1.0000x reference)
; __device__ __forceinline__ int tidx() { int t = threadIdx.x; asm volatile("" : "+v"(t)); return t; }
; #define LAS __attribute__((address_space(3)))
; __device__ __forceinline__ float bf2f(bf16_t b) { return __uint_as_float(((unsigned)b) << 16); }
; template <int V, bool GLA> __device__ __forceinline__ void rec_sample_item(const P& p, unsigned char* ws, int l, LAS unsigned char* lds, int b, int head) {
;     constexpr int nheads = GLA ? GH : HH, ldk = GLA ? GKW : HW, NV4 = V / 4, NCG = NTHR / NV4, CPG = 128 / NCG;
;     const int tid = tidx(); const size_t row = (size_t)(MP + b);
;     LAS float* DQ = (LAS float*)lds; LAS float* RED = (LAS float*)(lds + 2048);
;     __syncthreads();
;     if (tid < 128) {
;         DQ[tid] = __expf(((const float*)(ws + (GLA ? WS_LOGA : WS_LOGF)))[row * ldk + head * 128 + tid]);
;         DQ[128 + tid] = bf2f(((const bf16_t*)(ws + (GLA ? WS_KG : WS_KH)))[row * ldk + head * 128 + tid]);
;         DQ[256 + tid] = bf2f(((const bf16_t*)(ws + (GLA ? WS_QG : WS_QH)))[row * ldk + head * 128 + tid]);
;     }
;     __syncthreads();
;     const int v4 = tid % NV4, cg = tid / NV4;
;     const u32x2 vw = *(const u32x2*)((const bf16_t*)(ws + (GLA ? WS_VG : WS_VH)) + row * 1024 + head * V + v4 * 4);
;     const f32x4 vv = (f32x4){__uint_as_float(vw.x << 16), __uint_as_float(vw.x & 0xffff0000u), __uint_as_float(vw.y << 16), __uint_as_float(vw.y & 0xffff0000u)};
;     const size_t sbase = ((size_t)l * DECB * nheads + (size_t)b * nheads + head) * 128 * V;
;     const float* s0 = (GLA ? p.stg : p.sth) + sbase; float* so = p.out + (GLA ? OUT_GS : OUT_HS) + sbase;
;     f32x4 oacc = (f32x4){0.f, 0.f, 0.f, 0.f};
;     f32x4 sv[CPG];
; #pragma unroll
;     for (int i = 0; i < CPG; ++i) sv[i] = __builtin_nontemporal_load((const f32x4*)(s0 + (size_t)(cg * CPG + i) * V + v4 * 4));
.LBB0_1128:
	s_ashr_i32 s0, s39, 3
	s_add_i32 s16, s0, 0x2000
	s_and_b32 s41, s39, 7
	v_mov_b32_e32 v22, v0
	s_ashr_i32 s17, s16, 31
	s_lshl_b64 s[6:7], s[16:17], 10
	v_cmp_gt_i32_e32 vcc, s82, v22
	s_lshl_b32 s92, s41, 7
	v_ashrrev_i32_e32 v23, 31, v22
	v_lshl_add_u32 v42, v22, 2, 0
	s_waitcnt vmcnt(0)
	s_barrier
	s_and_saveexec_b64 s[28:29], vcc
	s_cbranch_execz .LBB0_1130
	s_or_b64 s[42:43], s[6:7], s[92:93]
	v_lshl_add_u64 v[2:3], s[42:43], 0, v[22:23]
	v_lshl_add_u64 v[4:5], v[2:3], 2, s[18:19]
	global_load_dword v6, v[4:5], off
	v_lshlrev_b64 v[2:3], 1, v[2:3]
	v_lshl_add_u64 v[4:5], s[20:21], 0, v[2:3]
	v_lshl_add_u64 v[2:3], s[22:23], 0, v[2:3]
	global_load_ushort v4, v[4:5], off
	s_nop 0
	global_load_ushort v2, v[2:3], off
	s_waitcnt vmcnt(2)
	v_mul_f32_e32 v6, 0x3fb8aa3b, v6
	v_exp_f32_e32 v6, v6
	s_waitcnt vmcnt(1)
	v_lshlrev_b32_e32 v4, 16, v4
	s_nop 0
	ds_write2st64_b32 v42, v6, v4 offset1:2
	s_waitcnt vmcnt(0)
	v_lshlrev_b32_e32 v2, 16, v2
	ds_write_b32 v42, v2 offset:1024
.LBB0_1130:
	s_or_b64 exec, exec, s[28:29]
	v_lshrrev_b32_e32 v2, 27, v23
	v_add_u32_e32 v2, v22, v2
	s_lshl_b64 s[28:29], s[6:7], 1
	v_and_b32_e32 v16, 0xffffffe0, v2
	s_add_u32 s1, s34, s28
	v_sub_u32_e32 v44, v22, v16
	s_addc_u32 s7, s35, s29
	s_lshl_b32 s40, s92, 1
	v_ashrrev_i32_e32 v43, 5, v2
	s_add_u32 s6, s1, s40
	v_lshlrev_b32_e32 v2, 2, v44
	s_addc_u32 s7, s7, 0
	v_ashrrev_i32_e32 v3, 31, v2
	v_lshl_add_u64 v[4:5], v[2:3], 1, s[6:7]
	s_waitcnt lgkmcnt(0)
	s_barrier
	global_load_dwordx2 v[254:255], v[4:5], off
	s_ashr_i32 s1, s0, 31
	s_lshl_b64 s[0:1], s[0:1], 3
	s_add_u32 s0, s0, s24
	s_addc_u32 s1, s1, s25
	s_or_b32 s0, s0, s41
	s_lshl_b64 s[0:1], s[0:1], 16
	s_add_u32 s6, s89, s0
	s_addc_u32 s7, s88, s1
	v_lshlrev_b64 v[14:15], 2, v[2:3]
	v_lshl_add_u64 v[2:3], s[6:7], 0, v[14:15]
	v_add_u32_e32 v45, 0, v16
	s_add_u32 s0, s37, s0
	ds_read_b128 v[58:61], v45 offset:512
	s_addc_u32 s1, s38, s1
	v_lshl_add_u64 v[30:31], s[0:1], 0, v[14:15]
	s_movk_i32 s0, 0x1e0
	v_lshlrev_b32_e32 v4, 3, v43
	v_ashrrev_i32_e32 v5, 31, v4
	v_lshlrev_b64 v[66:67], 9, v[4:5]
	v_lshl_add_u64 v[6:7], v[2:3], 0, v[66:67]
	global_load_dwordx4 v[36:39], v[6:7], off nt
	v_or_b32_e32 v6, 1, v4
	v_ashrrev_i32_e32 v7, 31, v6
	v_lshlrev_b64 v[70:71], 9, v[6:7]
	v_lshl_add_u64 v[6:7], v[2:3], 0, v[70:71]
	global_load_dwordx4 v[46:49], v[6:7], off nt
	v_or_b32_e32 v6, 2, v4
	v_ashrrev_i32_e32 v7, 31, v6
	v_lshlrev_b64 v[72:73], 9, v[6:7]
	v_lshl_add_u64 v[6:7], v[2:3], 0, v[72:73]
	global_load_dwordx4 v[50:53], v[6:7], off nt
	v_or_b32_e32 v6, 3, v4
	v_ashrrev_i32_e32 v7, 31, v6
	v_lshlrev_b64 v[74:75], 9, v[6:7]
	v_lshl_add_u64 v[6:7], v[2:3], 0, v[74:75]
	global_load_dwordx4 v[54:57], v[6:7], off nt
	v_or_b32_e32 v6, 4, v4
	v_ashrrev_i32_e32 v7, 31, v6
	v_lshlrev_b64 v[40:41], 9, v[6:7]
	v_lshl_add_u64 v[6:7], v[2:3], 0, v[40:41]
	global_load_dwordx4 v[18:21], v[6:7], off nt
	v_or_b32_e32 v6, 5, v4
	v_ashrrev_i32_e32 v7, 31, v6
	v_lshlrev_b64 v[34:35], 9, v[6:7]
	v_lshl_add_u64 v[6:7], v[2:3], 0, v[34:35]
	global_load_dwordx4 v[10:13], v[6:7], off nt
	v_or_b32_e32 v6, 6, v4
	v_ashrrev_i32_e32 v7, 31, v6
	v_lshlrev_b64 v[32:33], 9, v[6:7]
	v_lshl_add_u64 v[6:7], v[2:3], 0, v[32:33]
	v_or_b32_e32 v4, 7, v4
	global_load_dwordx4 v[6:9], v[6:7], off nt
	v_ashrrev_i32_e32 v5, 31, v4
	v_lshlrev_b64 v[28:29], 9, v[4:5]
	v_lshl_add_u64 v[2:3], v[2:3], 0, v[28:29]
	global_load_dwordx4 v[2:5], v[2:3], off nt
	s_waitcnt vmcnt(8)
	v_lshlrev_b32_e32 v24, 16, v254
	v_and_b32_e32 v25, 0xffff0000, v254
	v_lshlrev_b32_e32 v26, 16, v255
	v_and_b32_e32 v27, 0xffff0000, v255
	ds_read_b128 v[62:65], v45
	ds_read_b128 v[14:17], v45 offset:16
	s_waitcnt lgkmcnt(2)
	v_pk_mul_f32 v[68:69], v[58:59], v[24:25] op_sel_hi:[0,1]
	v_pk_mul_f32 v[76:77], v[58:59], v[26:27] op_sel_hi:[0,1]
	v_lshl_add_u64 v[66:67], v[30:31], 0, v[66:67]
	v_lshl_add_u64 v[40:41], v[30:31], 0, v[40:41]
	s_waitcnt vmcnt(7) lgkmcnt(1)
	v_pk_fma_f32 v[38:39], v[38:39], v[62:63], v[76:77] op_sel_hi:[1,0,1]
	v_pk_fma_f32 v[36:37], v[36:37], v[62:63], v[68:69] op_sel_hi:[1,0,1]
	global_store_dwordx4 v[66:67], v[36:39], off nt
	ds_read_b128 v[66:69], v45 offset:1024
	s_waitcnt lgkmcnt(0)
	v_pk_fma_f32 v[76:77], v[38:39], v[66:67], 0 op_sel_hi:[1,0,0]
	v_pk_fma_f32 v[78:79], v[36:37], v[66:67], 0 op_sel_hi:[1,0,0]
	v_pk_mul_f32 v[36:37], v[58:59], v[24:25] op_sel:[1,0]
	v_pk_mul_f32 v[38:39], v[58:59], v[26:27] op_sel:[1,0]
	s_waitcnt vmcnt(7)
; #define LAS __attribute__((address_space(3)))
; template <int V, bool GLA> __device__ __forceinline__ void rec_sample_item(const P& p, unsigned char* ws, int l, LAS unsigned char* lds, int b, int head) {
;     ...
; #pragma unroll
;     for (int i = 0; i < CPG; ++i) { const int cc = cg * CPG + i; const f32x4 sn = sv[i] * DQ[cc] + vv * DQ[128 + cc]; __builtin_nontemporal_store(sn, (f32x4*)(so + (size_t)cc * V + v4 * 4)); oacc += sn * DQ[256 + cc]; }
;     *(LAS f32x4*)(RED + cg * V + v4 * 4) = oacc;
;     __syncthreads();
;     float s = 0.f;
;     if (tid < V) {
; #pragma unroll
;         for (int g = 0; g < NCG; ++g) s += RED[g * V + tid]; }
	v_pk_fma_f32 v[36:37], v[46:47], v[62:63], v[36:37] op_sel:[0,1,0]
	v_pk_fma_f32 v[38:39], v[48:49], v[62:63], v[38:39] op_sel:[0,1,0]
	v_lshl_add_u64 v[46:47], v[30:31], 0, v[70:71]
	global_store_dwordx4 v[46:47], v[36:39], off nt
	v_pk_fma_f32 v[46:47], v[38:39], v[66:67], v[76:77] op_sel:[0,1,0]
	v_pk_fma_f32 v[48:49], v[36:37], v[66:67], v[78:79] op_sel:[0,1,0]
	v_pk_mul_f32 v[36:37], v[60:61], v[24:25] op_sel_hi:[0,1]
	v_pk_mul_f32 v[38:39], v[60:61], v[26:27] op_sel_hi:[0,1]
	s_waitcnt vmcnt(7)
	v_pk_fma_f32 v[38:39], v[52:53], v[64:65], v[38:39] op_sel_hi:[1,0,1]
	v_pk_fma_f32 v[36:37], v[50:51], v[64:65], v[36:37] op_sel_hi:[1,0,1]
	v_lshl_add_u64 v[50:51], v[30:31], 0, v[72:73]
	global_store_dwordx4 v[50:51], v[36:39], off nt
	v_pk_fma_f32 v[50:51], v[36:37], v[68:69], v[48:49] op_sel_hi:[1,0,1]
	v_mov_b32_e32 v52, v65
	v_mov_b32_e32 v36, v61
	v_pk_fma_f32 v[38:39], v[38:39], v[68:69], v[46:47] op_sel_hi:[1,0,1]
	v_pk_mul_f32 v[46:47], v[36:37], v[24:25] op_sel_hi:[0,1]
	v_pk_mul_f32 v[36:37], v[36:37], v[26:27] op_sel_hi:[0,1]
	s_waitcnt vmcnt(7)
	v_pk_fma_f32 v[48:49], v[56:57], v[52:53], v[36:37] op_sel_hi:[1,0,1]
	v_pk_fma_f32 v[46:47], v[54:55], v[52:53], v[46:47] op_sel_hi:[1,0,1]
	v_lshl_add_u64 v[36:37], v[30:31], 0, v[74:75]
	v_mov_b32_e32 v52, v69
	global_store_dwordx4 v[36:37], v[46:49], off nt
	v_pk_fma_f32 v[36:37], v[48:49], v[52:53], v[38:39] op_sel_hi:[1,0,1]
	v_pk_fma_f32 v[38:39], v[46:47], v[52:53], v[50:51] op_sel_hi:[1,0,1]
	ds_read_b128 v[46:49], v45 offset:528
	s_waitcnt lgkmcnt(0)
	v_pk_mul_f32 v[50:51], v[46:47], v[24:25] op_sel_hi:[0,1]
	v_pk_mul_f32 v[52:53], v[46:47], v[26:27] op_sel_hi:[0,1]
	s_waitcnt vmcnt(7)
	v_pk_fma_f32 v[20:21], v[20:21], v[14:15], v[52:53] op_sel_hi:[1,0,1]
	v_pk_fma_f32 v[18:19], v[18:19], v[14:15], v[50:51] op_sel_hi:[1,0,1]
	ds_read_b128 v[50:53], v45 offset:1040
	global_store_dwordx4 v[40:41], v[18:21], off nt
	s_waitcnt lgkmcnt(0)
	s_nop 0
	v_pk_fma_f32 v[20:21], v[20:21], v[50:51], v[36:37] op_sel_hi:[1,0,1]
	v_pk_fma_f32 v[18:19], v[18:19], v[50:51], v[38:39] op_sel_hi:[1,0,1]
	v_pk_mul_f32 v[36:37], v[46:47], v[24:25] op_sel:[1,0]
	v_pk_mul_f32 v[38:39], v[46:47], v[26:27] op_sel:[1,0]
	s_waitcnt vmcnt(7)
	v_pk_fma_f32 v[10:11], v[10:11], v[14:15], v[36:37] op_sel:[0,1,0]
	v_pk_fma_f32 v[12:13], v[12:13], v[14:15], v[38:39] op_sel:[0,1,0]
	v_lshl_add_u64 v[14:15], v[30:31], 0, v[34:35]
	global_store_dwordx4 v[14:15], v[10:13], off nt
	v_pk_mul_f32 v[14:15], v[48:49], v[24:25] op_sel_hi:[0,1]
	s_waitcnt vmcnt(7)
	v_pk_fma_f32 v[6:7], v[6:7], v[16:17], v[14:15] op_sel_hi:[1,0,1]
	v_pk_fma_f32 v[10:11], v[10:11], v[50:51], v[18:19] op_sel:[0,1,0]
	v_pk_mul_f32 v[18:19], v[48:49], v[26:27] op_sel_hi:[0,1]
	v_pk_fma_f32 v[8:9], v[8:9], v[16:17], v[18:19] op_sel_hi:[1,0,1]
	v_lshl_add_u64 v[14:15], v[30:31], 0, v[32:33]
	v_pk_fma_f32 v[12:13], v[12:13], v[50:51], v[20:21] op_sel:[0,1,0]
	global_store_dwordx4 v[14:15], v[6:9], off nt
	v_mov_b32_e32 v14, v17
	s_nop 0
	v_pk_fma_f32 v[6:7], v[6:7], v[52:53], v[10:11] op_sel_hi:[1,0,1]
	v_mov_b32_e32 v10, v49
	v_pk_fma_f32 v[8:9], v[8:9], v[52:53], v[12:13] op_sel_hi:[1,0,1]
	v_pk_mul_f32 v[12:13], v[10:11], v[24:25] op_sel_hi:[0,1]
	v_pk_mul_f32 v[10:11], v[10:11], v[26:27] op_sel_hi:[0,1]
	s_waitcnt vmcnt(7)
	v_pk_fma_f32 v[4:5], v[4:5], v[14:15], v[10:11] op_sel_hi:[1,0,1]
	v_pk_fma_f32 v[2:3], v[2:3], v[14:15], v[12:13] op_sel_hi:[1,0,1]
	v_lshl_add_u64 v[10:11], v[30:31], 0, v[28:29]
	global_store_dwordx4 v[10:11], v[2:5], off nt
	v_mov_b32_e32 v10, v53
	s_nop 0
	v_pk_fma_f32 v[2:3], v[2:3], v[10:11], v[6:7] op_sel_hi:[1,0,1]
	v_mul_lo_u32 v6, v43, s0
	v_lshlrev_b32_e32 v7, 4, v44
	v_pk_fma_f32 v[4:5], v[4:5], v[10:11], v[8:9] op_sel_hi:[1,0,1]
	v_add3_u32 v6, v45, v6, v7
	ds_write_b128 v6, v[2:5] offset:2048
	v_mov_b32_e32 v2, 0
	s_waitcnt lgkmcnt(0)
	s_barrier
	s_and_saveexec_b64 s[0:1], vcc
	s_cbranch_execz .LBB0_1132
	ds_read2st64_b32 v[2:3], v42 offset0:8 offset1:10
	s_waitcnt lgkmcnt(0)
	v_add_f32_e32 v2, 0, v2
	v_add_f32_e32 v4, v2, v3
	ds_read2st64_b32 v[2:3], v42 offset0:12 offset1:14
	s_waitcnt lgkmcnt(0)
	v_add_f32_e32 v2, v4, v2
	v_add_f32_e32 v4, v2, v3
	ds_read2st64_b32 v[2:3], v42 offset0:16 offset1:18
	s_waitcnt lgkmcnt(0)
	v_add_f32_e32 v2, v4, v2
	v_add_f32_e32 v4, v2, v3
	ds_read2st64_b32 v[2:3], v42 offset0:20 offset1:22
	s_waitcnt lgkmcnt(0)
	v_add_f32_e32 v2, v4, v2
	v_add_f32_e32 v4, v2, v3
	ds_read2st64_b32 v[2:3], v42 offset0:24 offset1:26
	s_waitcnt lgkmcnt(0)
	v_add_f32_e32 v2, v4, v2
	v_add_f32_e32 v4, v2, v3
	ds_read2st64_b32 v[2:3], v42 offset0:28 offset1:30
	s_waitcnt lgkmcnt(0)
	v_add_f32_e32 v2, v4, v2
	v_add_f32_e32 v4, v2, v3
	ds_read2st64_b32 v[2:3], v42 offset0:32 offset1:34
	s_waitcnt lgkmcnt(0)
	v_add_f32_e32 v2, v4, v2
	v_add_f32_e32 v4, v2, v3
	ds_read2st64_b32 v[2:3], v42 offset0:36 offset1:38
	s_waitcnt lgkmcnt(0)
	v_add_f32_e32 v2, v4, v2
	v_add_f32_e32 v2, v2, v3

; __device__ __forceinline__ int tidx() { int t = threadIdx.x; asm volatile("" : "+v"(t)); return t; }
; #define LAS __attribute__((address_space(3)))
; __device__ __forceinline__ float bf2f(bf16_t b) { return __uint_as_float(((unsigned)b) << 16); }
; template <int V, bool GLA> __device__ __forceinline__ void rec_sample_item(const P& p, unsigned char* ws, int l, LAS unsigned char* lds, int b, int head) {
;     constexpr int nheads = GLA ? GH : HH, ldk = GLA ? GKW : HW, NV4 = V / 4, NCG = NTHR / NV4, CPG = 128 / NCG;
;     const int tid = tidx(); const size_t row = (size_t)(MP + b);
;     LAS float* DQ = (LAS float*)lds; LAS float* RED = (LAS float*)(lds + 2048);
;     __syncthreads();
;     if (tid < 128) {
;         DQ[tid] = __expf(((const float*)(ws + (GLA ? WS_LOGA : WS_LOGF)))[row * ldk + head * 128 + tid]);
;         DQ[128 + tid] = bf2f(((const bf16_t*)(ws + (GLA ? WS_KG : WS_KH)))[row * ldk + head * 128 + tid]);
;         DQ[256 + tid] = bf2f(((const bf16_t*)(ws + (GLA ? WS_QG : WS_QH)))[row * ldk + head * 128 + tid]);
;     }
;     __syncthreads();
;     const int v4 = tid % NV4, cg = tid / NV4;
;     const u32x2 vw = *(const u32x2*)((const bf16_t*)(ws + (GLA ? WS_VG : WS_VH)) + row * 1024 + head * V + v4 * 4);
;     const f32x4 vv = (f32x4){__uint_as_float(vw.x << 16), __uint_as_float(vw.x & 0xffff0000u), __uint_as_float(vw.y << 16), __uint_as_float(vw.y & 0xffff0000u)};
;     const size_t sbase = ((size_t)l * DECB * nheads + (size_t)b * nheads + head) * 128 * V;
;     const float* s0 = (GLA ? p.stg : p.sth) + sbase; float* so = p.out + (GLA ? OUT_GS : OUT_HS) + sbase;
;     f32x4 oacc = (f32x4){0.f, 0.f, 0.f, 0.f};
;     f32x4 sv[CPG];
; #pragma unroll
;     for (int i = 0; i < CPG; ++i) sv[i] = __builtin_nontemporal_load((const f32x4*)(s0 + (size_t)(cg * CPG + i) * V + v4 * 4));
.LBB0_1137:
	s_ashr_i32 s0, s72, 2
	v_mov_b32_e32 v66, v0
	s_add_i32 s14, s0, 0x2000
	s_and_b32 s30, s72, 3
	s_ashr_i32 s15, s14, 31
	v_cmp_gt_i32_e32 vcc, s82, v66
	v_ashrrev_i32_e32 v67, 31, v66
	v_lshl_add_u32 v106, v66, 2, 0
	s_waitcnt vmcnt(0)
	s_barrier
	s_and_saveexec_b64 s[6:7], vcc
	s_cbranch_execz .LBB0_1139
	s_lshl_b64 s[34:35], s[14:15], 9
	s_lshl_b32 s1, s30, 7
	s_or_b32 s34, s34, s1
	v_lshl_add_u64 v[2:3], s[34:35], 0, v[66:67]
	v_lshl_add_u64 v[4:5], v[2:3], 2, s[16:17]
	global_load_dword v6, v[4:5], off
	v_lshlrev_b64 v[2:3], 1, v[2:3]
	v_lshl_add_u64 v[4:5], s[18:19], 0, v[2:3]
	v_lshl_add_u64 v[2:3], s[20:21], 0, v[2:3]
	global_load_ushort v4, v[4:5], off
	s_nop 0
	global_load_ushort v2, v[2:3], off
	s_waitcnt vmcnt(2)
	v_mul_f32_e32 v6, 0x3fb8aa3b, v6
	v_exp_f32_e32 v6, v6
	s_waitcnt vmcnt(1)
	v_lshlrev_b32_e32 v4, 16, v4
	s_nop 0
	ds_write2st64_b32 v106, v6, v4 offset1:2
	s_waitcnt vmcnt(0)
	v_lshlrev_b32_e32 v2, 16, v2
	ds_write_b32 v106, v2 offset:1024
.LBB0_1139:
	s_or_b64 exec, exec, s[6:7]
	v_lshrrev_b32_e32 v2, 26, v67
	v_add_u32_e32 v2, v66, v2
	s_lshl_b64 s[6:7], s[14:15], 11
	v_and_b32_e32 v109, 0xffffffc0, v2
	s_add_u32 s1, s22, s6
	v_sub_u32_e32 v108, v66, v109
	s_addc_u32 s7, s23, s7
	s_lshl_b32 s6, s30, 9
	v_ashrrev_i32_e32 v107, 6, v2
	s_add_u32 s6, s1, s6
	v_lshlrev_b32_e32 v2, 2, v108
	s_addc_u32 s7, s7, 0
	v_ashrrev_i32_e32 v3, 31, v2
	v_lshl_add_u64 v[4:5], v[2:3], 1, s[6:7]
	s_waitcnt lgkmcnt(0)
	s_barrier
	global_load_dwordx2 v[254:255], v[4:5], off
	s_ashr_i32 s1, s0, 31
	s_lshl_b64 s[0:1], s[0:1], 2
	s_add_u32 s0, s0, s10
	s_addc_u32 s1, s1, s11
	s_or_b32 s0, s0, s30
	s_lshl_b64 s[0:1], s[0:1], 17
	s_add_u32 s6, s49, s0
	s_addc_u32 s7, s48, s1
	v_lshlrev_b64 v[74:75], 2, v[2:3]
	v_lshl_add_u64 v[2:3], s[6:7], 0, v[74:75]
	v_add_u32_e32 v109, 0, v109
	s_add_u32 s0, s28, s0
	s_addc_u32 s1, s29, s1
	v_lshl_add_u64 v[74:75], s[0:1], 0, v[74:75]
	s_movk_i32 s0, 0x3c0
	v_cmp_gt_i32_e32 vcc, s59, v66
	v_lshlrev_b32_e32 v4, 4, v107
	v_ashrrev_i32_e32 v5, 31, v4
	v_lshlrev_b64 v[98:99], 10, v[4:5]
	v_lshl_add_u64 v[6:7], v[2:3], 0, v[98:99]
	global_load_dwordx4 v[50:53], v[6:7], off nt
	v_or_b32_e32 v6, 1, v4
	v_ashrrev_i32_e32 v7, 31, v6
	v_lshlrev_b64 v[100:101], 10, v[6:7]
	v_lshl_add_u64 v[6:7], v[2:3], 0, v[100:101]
	global_load_dwordx4 v[54:57], v[6:7], off nt
	v_or_b32_e32 v6, 2, v4
	v_ashrrev_i32_e32 v7, 31, v6
	v_lshlrev_b64 v[102:103], 10, v[6:7]
	v_lshl_add_u64 v[6:7], v[2:3], 0, v[102:103]
	global_load_dwordx4 v[58:61], v[6:7], off nt
	v_or_b32_e32 v6, 3, v4
	v_ashrrev_i32_e32 v7, 31, v6
	v_lshlrev_b64 v[104:105], 10, v[6:7]
	v_lshl_add_u64 v[6:7], v[2:3], 0, v[104:105]
	global_load_dwordx4 v[62:65], v[6:7], off nt
	v_or_b32_e32 v6, 4, v4
	v_ashrrev_i32_e32 v7, 31, v6
	v_lshlrev_b64 v[94:95], 10, v[6:7]
	v_lshl_add_u64 v[6:7], v[2:3], 0, v[94:95]
	global_load_dwordx4 v[42:45], v[6:7], off nt
	v_or_b32_e32 v6, 5, v4
	v_ashrrev_i32_e32 v7, 31, v6
	v_lshlrev_b64 v[80:81], 10, v[6:7]
	v_lshl_add_u64 v[6:7], v[2:3], 0, v[80:81]
	global_load_dwordx4 v[14:17], v[6:7], off nt
	v_or_b32_e32 v6, 6, v4
	v_ashrrev_i32_e32 v7, 31, v6
	v_lshlrev_b64 v[84:85], 10, v[6:7]
	v_lshl_add_u64 v[6:7], v[2:3], 0, v[84:85]
	global_load_dwordx4 v[22:25], v[6:7], off nt
	v_or_b32_e32 v6, 7, v4
	v_ashrrev_i32_e32 v7, 31, v6
	v_lshlrev_b64 v[86:87], 10, v[6:7]
	v_lshl_add_u64 v[6:7], v[2:3], 0, v[86:87]
	global_load_dwordx4 v[26:29], v[6:7], off nt
	v_or_b32_e32 v6, 8, v4
	v_ashrrev_i32_e32 v7, 31, v6
	v_lshlrev_b64 v[82:83], 10, v[6:7]
	v_lshl_add_u64 v[6:7], v[2:3], 0, v[82:83]
	global_load_dwordx4 v[18:21], v[6:7], off nt
	v_or_b32_e32 v6, 9, v4
	v_ashrrev_i32_e32 v7, 31, v6
	v_lshlrev_b64 v[88:89], 10, v[6:7]
	v_lshl_add_u64 v[6:7], v[2:3], 0, v[88:89]
	global_load_dwordx4 v[30:33], v[6:7], off nt
	v_or_b32_e32 v6, 10, v4
	v_ashrrev_i32_e32 v7, 31, v6
	v_lshlrev_b64 v[90:91], 10, v[6:7]
	v_lshl_add_u64 v[6:7], v[2:3], 0, v[90:91]
	global_load_dwordx4 v[34:37], v[6:7], off nt
	v_or_b32_e32 v6, 11, v4
	v_ashrrev_i32_e32 v7, 31, v6
	v_lshlrev_b64 v[96:97], 10, v[6:7]
	v_lshl_add_u64 v[6:7], v[2:3], 0, v[96:97]
	global_load_dwordx4 v[46:49], v[6:7], off nt
	v_or_b32_e32 v6, 12, v4
	v_ashrrev_i32_e32 v7, 31, v6
	v_lshlrev_b64 v[92:93], 10, v[6:7]
	v_lshl_add_u64 v[6:7], v[2:3], 0, v[92:93]
	global_load_dwordx4 v[38:41], v[6:7], off nt
	v_or_b32_e32 v6, 13, v4
	v_ashrrev_i32_e32 v7, 31, v6
	v_lshlrev_b64 v[78:79], 10, v[6:7]
	v_lshl_add_u64 v[6:7], v[2:3], 0, v[78:79]
	global_load_dwordx4 v[10:13], v[6:7], off nt
	v_or_b32_e32 v6, 14, v4
	v_ashrrev_i32_e32 v7, 31, v6
	v_lshlrev_b64 v[76:77], 10, v[6:7]
	v_lshl_add_u64 v[6:7], v[2:3], 0, v[76:77]
	v_or_b32_e32 v4, 15, v4
	global_load_dwordx4 v[6:9], v[6:7], off nt
	v_ashrrev_i32_e32 v5, 31, v4
	v_lshlrev_b64 v[72:73], 10, v[4:5]
	v_lshl_add_u64 v[2:3], v[2:3], 0, v[72:73]
	global_load_dwordx4 v[2:5], v[2:3], off nt
	s_waitcnt vmcnt(16)
	v_lshlrev_b32_e32 v68, 16, v254
	v_and_b32_e32 v69, 0xffff0000, v254
	v_lshlrev_b32_e32 v70, 16, v255
	v_and_b32_e32 v71, 0xffff0000, v255
	ds_read_b128 v[110:113], v109
	ds_read_b128 v[114:117], v109 offset:512
	v_lshl_add_u64 v[98:99], v[74:75], 0, v[98:99]
	v_lshl_add_u64 v[94:95], v[74:75], 0, v[94:95]
	s_waitcnt lgkmcnt(0)
	v_pk_mul_f32 v[118:119], v[114:115], v[68:69] op_sel_hi:[0,1]
	v_pk_mul_f32 v[120:121], v[114:115], v[70:71] op_sel_hi:[0,1]
	s_waitcnt vmcnt(15)
	v_pk_fma_f32 v[52:53], v[52:53], v[110:111], v[120:121] op_sel_hi:[1,0,1]
	v_pk_fma_f32 v[50:51], v[50:51], v[110:111], v[118:119] op_sel_hi:[1,0,1]
	ds_read_b128 v[118:121], v109 offset:1024
	global_store_dwordx4 v[98:99], v[50:53], off nt
	s_waitcnt lgkmcnt(0)
; #define LAS __attribute__((address_space(3)))
; template <int V, bool GLA> __device__ __forceinline__ void rec_sample_item(const P& p, unsigned char* ws, int l, LAS unsigned char* lds, int b, int head) {
;     ...
; #pragma unroll
;     for (int i = 0; i < CPG; ++i) { const int cc = cg * CPG + i; const f32x4 sn = sv[i] * DQ[cc] + vv * DQ[128 + cc]; __builtin_nontemporal_store(sn, (f32x4*)(so + (size_t)cc * V + v4 * 4)); oacc += sn * DQ[256 + cc]; }
;     *(LAS f32x4*)(RED + cg * V + v4 * 4) = oacc;
	v_pk_fma_f32 v[98:99], v[52:53], v[118:119], 0 op_sel_hi:[1,0,0]
	v_pk_fma_f32 v[122:123], v[50:51], v[118:119], 0 op_sel_hi:[1,0,0]
	v_pk_mul_f32 v[50:51], v[114:115], v[68:69] op_sel:[1,0]
	v_pk_mul_f32 v[52:53], v[114:115], v[70:71] op_sel:[1,0]
	s_waitcnt vmcnt(15)
	v_pk_fma_f32 v[50:51], v[54:55], v[110:111], v[50:51] op_sel:[0,1,0]
	v_pk_fma_f32 v[52:53], v[56:57], v[110:111], v[52:53] op_sel:[0,1,0]
	v_lshl_add_u64 v[54:55], v[74:75], 0, v[100:101]
	global_store_dwordx4 v[54:55], v[50:53], off nt
	v_pk_fma_f32 v[54:55], v[52:53], v[118:119], v[98:99] op_sel:[0,1,0]
	v_pk_fma_f32 v[56:57], v[50:51], v[118:119], v[122:123] op_sel:[0,1,0]
	v_pk_mul_f32 v[50:51], v[116:117], v[68:69] op_sel_hi:[0,1]
	v_pk_mul_f32 v[52:53], v[116:117], v[70:71] op_sel_hi:[0,1]
	s_waitcnt vmcnt(15)
	v_pk_fma_f32 v[52:53], v[60:61], v[112:113], v[52:53] op_sel_hi:[1,0,1]
	v_pk_fma_f32 v[50:51], v[58:59], v[112:113], v[50:51] op_sel_hi:[1,0,1]
	v_lshl_add_u64 v[58:59], v[74:75], 0, v[102:103]
	global_store_dwordx4 v[58:59], v[50:53], off nt
	v_pk_fma_f32 v[56:57], v[50:51], v[120:121], v[56:57] op_sel_hi:[1,0,1]
	v_mov_b32_e32 v60, v113
	v_mov_b32_e32 v50, v117
	v_pk_mul_f32 v[58:59], v[50:51], v[68:69] op_sel_hi:[0,1]
	v_pk_mul_f32 v[50:51], v[50:51], v[70:71] op_sel_hi:[0,1]
	v_pk_fma_f32 v[54:55], v[52:53], v[120:121], v[54:55] op_sel_hi:[1,0,1]
	s_waitcnt vmcnt(15)
	v_pk_fma_f32 v[52:53], v[64:65], v[60:61], v[50:51] op_sel_hi:[1,0,1]
	v_pk_fma_f32 v[50:51], v[62:63], v[60:61], v[58:59] op_sel_hi:[1,0,1]
	v_lshl_add_u64 v[58:59], v[74:75], 0, v[104:105]
	global_store_dwordx4 v[58:59], v[50:53], off nt
	v_mov_b32_e32 v58, v121
	v_pk_fma_f32 v[54:55], v[52:53], v[58:59], v[54:55] op_sel_hi:[1,0,1]
	v_pk_fma_f32 v[56:57], v[50:51], v[58:59], v[56:57] op_sel_hi:[1,0,1]
	ds_read_b128 v[58:61], v109 offset:528
	ds_read_b128 v[62:65], v109 offset:16
	ds_read_b128 v[50:53], v109 offset:32
	s_waitcnt lgkmcnt(2)
	v_pk_mul_f32 v[98:99], v[58:59], v[68:69] op_sel_hi:[0,1]
	v_pk_mul_f32 v[100:101], v[58:59], v[70:71] op_sel_hi:[0,1]
	s_waitcnt vmcnt(15) lgkmcnt(1)
	v_pk_fma_f32 v[44:45], v[44:45], v[62:63], v[100:101] op_sel_hi:[1,0,1]
	v_pk_fma_f32 v[42:43], v[42:43], v[62:63], v[98:99] op_sel_hi:[1,0,1]
	ds_read_b128 v[98:101], v109 offset:1040
	global_store_dwordx4 v[94:95], v[42:45], off nt
	s_waitcnt lgkmcnt(0)
	s_nop 0
	v_pk_fma_f32 v[44:45], v[44:45], v[98:99], v[54:55] op_sel_hi:[1,0,1]
	v_pk_fma_f32 v[42:43], v[42:43], v[98:99], v[56:57] op_sel_hi:[1,0,1]
	v_pk_mul_f32 v[54:55], v[58:59], v[68:69] op_sel:[1,0]
	v_pk_mul_f32 v[56:57], v[58:59], v[70:71] op_sel:[1,0]
	s_waitcnt vmcnt(15)
	v_pk_fma_f32 v[14:15], v[14:15], v[62:63], v[54:55] op_sel:[0,1,0]
	v_pk_fma_f32 v[16:17], v[16:17], v[62:63], v[56:57] op_sel:[0,1,0]
	v_lshl_add_u64 v[54:55], v[74:75], 0, v[80:81]
	global_store_dwordx4 v[54:55], v[14:17], off nt
	v_pk_fma_f32 v[44:45], v[16:17], v[98:99], v[44:45] op_sel:[0,1,0]
	v_pk_fma_f32 v[42:43], v[14:15], v[98:99], v[42:43] op_sel:[0,1,0]
	v_pk_mul_f32 v[14:15], v[60:61], v[68:69] op_sel_hi:[0,1]
	v_pk_mul_f32 v[16:17], v[60:61], v[70:71] op_sel_hi:[0,1]
	s_waitcnt vmcnt(15)
	v_pk_fma_f32 v[16:17], v[24:25], v[64:65], v[16:17] op_sel_hi:[1,0,1]
	v_pk_fma_f32 v[14:15], v[22:23], v[64:65], v[14:15] op_sel_hi:[1,0,1]
	v_lshl_add_u64 v[22:23], v[74:75], 0, v[84:85]
	global_store_dwordx4 v[22:23], v[14:17], off nt
	v_pk_fma_f32 v[24:25], v[14:15], v[100:101], v[42:43] op_sel_hi:[1,0,1]
	v_pk_fma_f32 v[22:23], v[16:17], v[100:101], v[44:45] op_sel_hi:[1,0,1]
	v_mov_b32_e32 v14, v61
	v_pk_mul_f32 v[42:43], v[14:15], v[68:69] op_sel_hi:[0,1]
	v_pk_mul_f32 v[14:15], v[14:15], v[70:71] op_sel_hi:[0,1]
	v_mov_b32_e32 v44, v65
	s_waitcnt vmcnt(15)
	v_pk_fma_f32 v[16:17], v[28:29], v[44:45], v[14:15] op_sel_hi:[1,0,1]
	v_pk_fma_f32 v[14:15], v[26:27], v[44:45], v[42:43] op_sel_hi:[1,0,1]
	v_lshl_add_u64 v[26:27], v[74:75], 0, v[86:87]
	global_store_dwordx4 v[26:27], v[14:17], off nt
	v_mov_b32_e32 v26, v101
	v_pk_fma_f32 v[28:29], v[16:17], v[26:27], v[22:23] op_sel_hi:[1,0,1]
	v_pk_fma_f32 v[26:27], v[14:15], v[26:27], v[24:25] op_sel_hi:[1,0,1]
	ds_read_b128 v[14:17], v109 offset:544
	s_waitcnt lgkmcnt(0)
	v_pk_mul_f32 v[22:23], v[14:15], v[68:69] op_sel_hi:[0,1]
	v_pk_mul_f32 v[24:25], v[14:15], v[70:71] op_sel_hi:[0,1]
	s_waitcnt vmcnt(15)
	v_pk_fma_f32 v[20:21], v[20:21], v[50:51], v[24:25] op_sel_hi:[1,0,1]
	v_pk_fma_f32 v[18:19], v[18:19], v[50:51], v[22:23] op_sel_hi:[1,0,1]
	v_lshl_add_u64 v[22:23], v[74:75], 0, v[82:83]
	global_store_dwordx4 v[22:23], v[18:21], off nt
	ds_read_b128 v[22:25], v109 offset:1056
	s_waitcnt lgkmcnt(0)
; #define LAS __attribute__((address_space(3)))
; template <int V, bool GLA> __device__ __forceinline__ void rec_sample_item(const P& p, unsigned char* ws, int l, LAS unsigned char* lds, int b, int head) {
;     ...
; #pragma unroll
;     for (int i = 0; i < CPG; ++i) { const int cc = cg * CPG + i; const f32x4 sn = sv[i] * DQ[cc] + vv * DQ[128 + cc]; __builtin_nontemporal_store(sn, (f32x4*)(so + (size_t)cc * V + v4 * 4)); oacc += sn * DQ[256 + cc]; }
;     *(LAS f32x4*)(RED + cg * V + v4 * 4) = oacc;
;     __syncthreads();
;     float s = 0.f;
;     if (tid < V) {
; #pragma unroll
;         for (int g = 0; g < NCG; ++g) s += RED[g * V + tid]; }
	v_pk_fma_f32 v[26:27], v[18:19], v[22:23], v[26:27] op_sel_hi:[1,0,1]
	v_pk_mul_f32 v[18:19], v[14:15], v[68:69] op_sel:[1,0]
	v_pk_mul_f32 v[14:15], v[14:15], v[70:71] op_sel:[1,0]
	v_pk_fma_f32 v[28:29], v[20:21], v[22:23], v[28:29] op_sel_hi:[1,0,1]
	s_waitcnt vmcnt(15)
	v_pk_fma_f32 v[20:21], v[32:33], v[50:51], v[14:15] op_sel:[0,1,0]
	v_pk_fma_f32 v[18:19], v[30:31], v[50:51], v[18:19] op_sel:[0,1,0]
	v_lshl_add_u64 v[14:15], v[74:75], 0, v[88:89]
	global_store_dwordx4 v[14:15], v[18:21], off nt
	v_pk_fma_f32 v[14:15], v[20:21], v[22:23], v[28:29] op_sel:[0,1,0]
	v_pk_fma_f32 v[22:23], v[18:19], v[22:23], v[26:27] op_sel:[0,1,0]
	v_pk_mul_f32 v[18:19], v[16:17], v[68:69] op_sel_hi:[0,1]
	v_pk_mul_f32 v[20:21], v[16:17], v[70:71] op_sel_hi:[0,1]
	s_waitcnt vmcnt(15)
	v_pk_fma_f32 v[20:21], v[36:37], v[52:53], v[20:21] op_sel_hi:[1,0,1]
	v_pk_fma_f32 v[18:19], v[34:35], v[52:53], v[18:19] op_sel_hi:[1,0,1]
	v_lshl_add_u64 v[26:27], v[74:75], 0, v[90:91]
	global_store_dwordx4 v[26:27], v[18:21], off nt
	v_pk_fma_f32 v[22:23], v[18:19], v[24:25], v[22:23] op_sel_hi:[1,0,1]
	v_lshl_add_u64 v[30:31], v[74:75], 0, v[92:93]
	v_pk_fma_f32 v[20:21], v[20:21], v[24:25], v[14:15] op_sel_hi:[1,0,1]
	v_mov_b32_e32 v14, v17
	v_pk_mul_f32 v[18:19], v[14:15], v[68:69] op_sel_hi:[0,1]
	v_pk_mul_f32 v[14:15], v[14:15], v[70:71] op_sel_hi:[0,1]
	v_mov_b32_e32 v24, v53
	s_waitcnt vmcnt(15)
	v_pk_fma_f32 v[16:17], v[48:49], v[24:25], v[14:15] op_sel_hi:[1,0,1]
	v_pk_fma_f32 v[14:15], v[46:47], v[24:25], v[18:19] op_sel_hi:[1,0,1]
	v_lshl_add_u64 v[18:19], v[74:75], 0, v[96:97]
	global_store_dwordx4 v[18:19], v[14:17], off nt
	v_mov_b32_e32 v24, v25
	v_pk_fma_f32 v[18:19], v[16:17], v[24:25], v[20:21] op_sel_hi:[1,0,1]
	v_pk_fma_f32 v[20:21], v[14:15], v[24:25], v[22:23] op_sel_hi:[1,0,1]
	ds_read_b128 v[14:17], v109 offset:48
	ds_read_b128 v[22:25], v109 offset:560
	s_waitcnt lgkmcnt(0)
	v_pk_mul_f32 v[26:27], v[22:23], v[68:69] op_sel_hi:[0,1]
	v_pk_mul_f32 v[28:29], v[22:23], v[70:71] op_sel_hi:[0,1]
	s_waitcnt vmcnt(15)
	v_pk_fma_f32 v[28:29], v[40:41], v[14:15], v[28:29] op_sel_hi:[1,0,1]
	v_pk_fma_f32 v[26:27], v[38:39], v[14:15], v[26:27] op_sel_hi:[1,0,1]
	global_store_dwordx4 v[30:31], v[26:29], off nt
	ds_read_b128 v[30:33], v109 offset:1072
	s_waitcnt lgkmcnt(0)
	v_pk_fma_f32 v[20:21], v[26:27], v[30:31], v[20:21] op_sel_hi:[1,0,1]
	v_pk_mul_f32 v[26:27], v[22:23], v[68:69] op_sel:[1,0]
	v_pk_mul_f32 v[22:23], v[22:23], v[70:71] op_sel:[1,0]
	v_pk_fma_f32 v[18:19], v[28:29], v[30:31], v[18:19] op_sel_hi:[1,0,1]
	s_waitcnt vmcnt(15)
	v_pk_fma_f32 v[12:13], v[12:13], v[14:15], v[22:23] op_sel:[0,1,0]
	v_pk_fma_f32 v[10:11], v[10:11], v[14:15], v[26:27] op_sel:[0,1,0]
	v_lshl_add_u64 v[14:15], v[74:75], 0, v[78:79]
	global_store_dwordx4 v[14:15], v[10:13], off nt
	v_pk_mul_f32 v[14:15], v[24:25], v[68:69] op_sel_hi:[0,1]
	s_waitcnt vmcnt(15)
	v_pk_fma_f32 v[6:7], v[6:7], v[16:17], v[14:15] op_sel_hi:[1,0,1]
	v_pk_fma_f32 v[12:13], v[12:13], v[30:31], v[18:19] op_sel:[0,1,0]
	v_pk_mul_f32 v[18:19], v[24:25], v[70:71] op_sel_hi:[0,1]
	v_pk_fma_f32 v[10:11], v[10:11], v[30:31], v[20:21] op_sel:[0,1,0]
	v_pk_fma_f32 v[8:9], v[8:9], v[16:17], v[18:19] op_sel_hi:[1,0,1]
	v_lshl_add_u64 v[14:15], v[74:75], 0, v[76:77]
	global_store_dwordx4 v[14:15], v[6:9], off nt
	v_mov_b32_e32 v14, v17
	s_nop 0
	v_pk_fma_f32 v[6:7], v[6:7], v[32:33], v[10:11] op_sel_hi:[1,0,1]
	v_mov_b32_e32 v10, v25
	v_pk_fma_f32 v[8:9], v[8:9], v[32:33], v[12:13] op_sel_hi:[1,0,1]
	v_pk_mul_f32 v[12:13], v[10:11], v[68:69] op_sel_hi:[0,1]
	v_pk_mul_f32 v[10:11], v[10:11], v[70:71] op_sel_hi:[0,1]
	s_waitcnt vmcnt(15)
	v_pk_fma_f32 v[4:5], v[4:5], v[14:15], v[10:11] op_sel_hi:[1,0,1]
	v_pk_fma_f32 v[2:3], v[2:3], v[14:15], v[12:13] op_sel_hi:[1,0,1]
	v_lshl_add_u64 v[10:11], v[74:75], 0, v[72:73]
	global_store_dwordx4 v[10:11], v[2:5], off nt
	v_mov_b32_e32 v10, v33
	s_nop 0
	v_pk_fma_f32 v[2:3], v[2:3], v[10:11], v[6:7] op_sel_hi:[1,0,1]
	v_mul_lo_u32 v6, v107, s0
	v_lshlrev_b32_e32 v7, 4, v108
	v_pk_fma_f32 v[4:5], v[4:5], v[10:11], v[8:9] op_sel_hi:[1,0,1]
	v_add3_u32 v6, v109, v6, v7
	ds_write_b128 v6, v[2:5] offset:2048
	v_mov_b32_e32 v2, 0
	s_waitcnt lgkmcnt(0)
	s_barrier
	s_and_saveexec_b64 s[0:1], vcc
	s_cbranch_execz .LBB0_1141
	ds_read2st64_b32 v[2:3], v106 offset0:8 offset1:12
	s_waitcnt lgkmcnt(0)
	v_add_f32_e32 v2, 0, v2
	v_add_f32_e32 v4, v2, v3
	ds_read2st64_b32 v[2:3], v106 offset0:16 offset1:20
	s_waitcnt lgkmcnt(0)
	v_add_f32_e32 v2, v4, v2
	v_add_f32_e32 v4, v2, v3
	ds_read2st64_b32 v[2:3], v106 offset0:24 offset1:28
	s_waitcnt lgkmcnt(0)
	v_add_f32_e32 v2, v4, v2
	v_add_f32_e32 v4, v2, v3
	ds_read2st64_b32 v[2:3], v106 offset0:32 offset1:36
	s_waitcnt lgkmcnt(0)
	v_add_f32_e32 v2, v4, v2
	v_add_f32_e32 v2, v2, v3
